# v87 + FFN1/SSDIn tile headers: 6 dead kernarg spill reloads per header removed (exact)
# baseline (speedup 1.0000x reference)
; template <class Epi, bool ALIGN_EPI = PG8_ALIGN, bool SP2 = PG8_SP2>
; __device__ __forceinline__ void gemm_phase(LAS uchar* lds, const Gemm g, const StaticOrder& S, const Epi& E) {
;     ...
;         const bool has_next = S.next(ui + 1, nxt);
;         const char* nA = has_next ? (const char*)g.A + (size_t)nxt.pm * tstepA : cA; const char* nB = has_next ? (const char*)g.Bt + (size_t)nxt.pn * tstepB : cB;
.LBB0_340:
	s_andn2_b64 s[0:1], exec, s[6:7]
	s_andn2_b64 vcc, exec, s[6:7]
	s_mov_b64 s[6:7], s[16:17]
	s_cbranch_vccnz .LBB0_342
	s_mul_i32 s6, s35, 0x88000
	v_readlane_b32 s44, v254, 4
	s_mul_hi_i32 s7, s35, 0x88000
	v_readlane_b32 s45, v254, 5
	s_add_u32 s6, s44, s6
	s_addc_u32 s7, s45, s7

; template <class Epi, bool ALIGN_EPI = PG8_ALIGN, bool SP2 = PG8_SP2>
; __device__ __forceinline__ void gemm_phase(LAS uchar* lds, const Gemm g, const StaticOrder& S, const Epi& E) {
;     ...
;         const bool has_next = S.next(ui + 1, nxt);
;         const char* nA = has_next ? (const char*)g.A + (size_t)nxt.pm * tstepA : cA; const char* nB = has_next ? (const char*)g.Bt + (size_t)nxt.pn * tstepB : cB;
.LBB0_1045:
	s_nop 0
	s_andn2_b64 s[4:5], exec, s[0:1]
	s_andn2_b64 vcc, exec, s[0:1]
	s_mov_b64 s[0:1], s[12:13]
	s_cbranch_vccnz .LBB0_1047
	s_mul_i32 s0, s31, 0x88000
	v_readlane_b32 s40, v254, 4
	s_mul_hi_i32 s1, s31, 0x88000
	v_readlane_b32 s41, v254, 5
	s_add_u32 s0, s40, s0
	s_addc_u32 s1, s41, s1
